# N0 bias GEMVs: the five per-row wave reductions interleaved (6 LDS round trips per row instead of 30)
# baseline (speedup 1.0000x reference)
.LBB0_180:
	global_load_dwordx4 v[98:101], v[86:87], off offset:-16
	global_load_dwordx4 v[106:109], v[86:87], off
	s_waitcnt vmcnt(1)
	v_and_b32_e32 v95, 0xffff0000, v98
	v_lshlrev_b32_e32 v93, 16, v98
	s_waitcnt lgkmcnt(0)
	v_lshlrev_b32_e32 v94, 16, v99
	v_and_b32_e32 v97, 0xffff0000, v99
	v_lshlrev_b32_e32 v96, 16, v100
	v_and_b32_e32 v99, 0xffff0000, v100
	s_waitcnt vmcnt(0)
	v_lshlrev_b32_e32 v100, 16, v106
	v_and_b32_e32 v103, 0xffff0000, v106
	v_lshlrev_b32_e32 v102, 16, v107
	v_and_b32_e32 v105, 0xffff0000, v107
	v_lshlrev_b32_e32 v104, 16, v108
	v_and_b32_e32 v107, 0xffff0000, v108
	v_lshlrev_b32_e32 v106, 16, v109
	v_and_b32_e32 v108, 0xffff0000, v109
	v_mul_f32_e32 v109, v1, v95
	v_mul_f32_e32 v110, v3, v97
	v_fmac_f32_e32 v109, v0, v93
	v_lshlrev_b32_e32 v98, 16, v101
	v_and_b32_e32 v101, 0xffff0000, v101
	v_mul_f32_e32 v111, v5, v99
	v_fmac_f32_e32 v110, v2, v94
	v_add_f32_e32 v109, 0, v109
	v_mul_f32_e32 v112, v7, v101
	v_fmac_f32_e32 v111, v4, v96
	v_add_f32_e32 v109, v110, v109
	v_mul_f32_e32 v113, v9, v103
	v_fmac_f32_e32 v112, v6, v98
	v_add_f32_e32 v109, v111, v109
	v_mul_f32_e32 v114, v11, v105
	v_fmac_f32_e32 v113, v8, v100
	v_add_f32_e32 v109, v112, v109
	v_mul_f32_e32 v115, v13, v107
	v_fmac_f32_e32 v114, v10, v102
	v_add_f32_e32 v109, v113, v109
	v_mul_f32_e32 v116, v15, v108
	v_fmac_f32_e32 v115, v12, v104
	v_add_f32_e32 v109, v114, v109
	v_add_f32_e32 v109, v115, v109
	v_fmac_f32_e32 v116, v14, v106
	v_add_f32_e32 v109, v116, v109
	v_mul_f32_e32 v118, v25, v95
	v_fmac_f32_e32 v118, v24, v93
	v_mul_f32_e32 v122, v27, v97
	v_add_f32_e32 v118, 0, v118
	v_fmac_f32_e32 v122, v26, v94
	v_add_f32_e32 v118, v122, v118
	v_mul_f32_e32 v122, v17, v99
	v_fmac_f32_e32 v122, v16, v96
	v_add_f32_e32 v118, v122, v118
	v_mul_f32_e32 v122, v19, v101
	v_fmac_f32_e32 v122, v18, v98
	v_add_f32_e32 v118, v122, v118
	v_mul_f32_e32 v122, v21, v103
	v_fmac_f32_e32 v122, v20, v100
	v_add_f32_e32 v118, v122, v118
	v_mul_f32_e32 v122, v23, v105
	v_fmac_f32_e32 v122, v22, v102
	v_add_f32_e32 v118, v122, v118
	v_mul_f32_e32 v122, v29, v107
	v_fmac_f32_e32 v122, v28, v104
	v_add_f32_e32 v118, v122, v118
	v_mul_f32_e32 v122, v31, v108
	v_fmac_f32_e32 v122, v30, v106
	v_add_f32_e32 v118, v122, v118
	v_mul_f32_e32 v119, v41, v95
	v_fmac_f32_e32 v119, v40, v93
	v_mul_f32_e32 v123, v43, v97
	v_add_f32_e32 v119, 0, v119
	v_fmac_f32_e32 v123, v42, v94
	v_add_f32_e32 v119, v123, v119
	v_mul_f32_e32 v123, v33, v99
	v_fmac_f32_e32 v123, v32, v96
	v_add_f32_e32 v119, v123, v119
	v_mul_f32_e32 v123, v35, v101
	v_fmac_f32_e32 v123, v34, v98
	v_add_f32_e32 v119, v123, v119
	v_mul_f32_e32 v123, v37, v103
	v_fmac_f32_e32 v123, v36, v100
	v_add_f32_e32 v119, v123, v119
	v_mul_f32_e32 v123, v39, v105
	v_fmac_f32_e32 v123, v38, v102
	v_add_f32_e32 v119, v123, v119
	v_mul_f32_e32 v123, v45, v107
	v_fmac_f32_e32 v123, v44, v104
	v_add_f32_e32 v119, v123, v119
	v_mul_f32_e32 v123, v47, v108
	v_fmac_f32_e32 v123, v46, v106
	v_add_f32_e32 v119, v123, v119
	v_mul_f32_e32 v120, v57, v95
	v_fmac_f32_e32 v120, v56, v93
	v_mul_f32_e32 v124, v59, v97
	v_add_f32_e32 v120, 0, v120
	v_fmac_f32_e32 v124, v58, v94
	v_add_f32_e32 v120, v124, v120
	v_mul_f32_e32 v124, v49, v99
	v_fmac_f32_e32 v124, v48, v96
	v_add_f32_e32 v120, v124, v120
	v_mul_f32_e32 v124, v51, v101
	v_fmac_f32_e32 v124, v50, v98
	v_add_f32_e32 v120, v124, v120
	v_mul_f32_e32 v124, v53, v103
	v_fmac_f32_e32 v124, v52, v100
	v_add_f32_e32 v120, v124, v120
	v_mul_f32_e32 v124, v55, v105
	v_fmac_f32_e32 v124, v54, v102
	v_add_f32_e32 v120, v124, v120
	v_mul_f32_e32 v124, v61, v107
	v_fmac_f32_e32 v124, v60, v104
	v_add_f32_e32 v120, v124, v120
	v_mul_f32_e32 v124, v63, v108
	v_fmac_f32_e32 v124, v62, v106
	v_add_f32_e32 v120, v124, v120
	v_mul_f32_e32 v95, v73, v95
	v_fmac_f32_e32 v95, v72, v93
	v_add_f32_e32 v93, 0, v95
	v_mul_f32_e32 v95, v75, v97
	v_fmac_f32_e32 v95, v74, v94
	v_mul_f32_e32 v94, v65, v99
	v_add_f32_e32 v93, v95, v93
	v_fmac_f32_e32 v94, v64, v96
	v_add_f32_e32 v93, v94, v93
	v_mul_f32_e32 v94, v67, v101
	v_fmac_f32_e32 v94, v66, v98
	v_add_f32_e32 v93, v94, v93
	v_mul_f32_e32 v94, v69, v103
	v_fmac_f32_e32 v94, v68, v100
	v_add_f32_e32 v93, v94, v93
	v_mul_f32_e32 v94, v71, v105
	v_fmac_f32_e32 v94, v70, v102
	v_add_f32_e32 v93, v94, v93
	v_mul_f32_e32 v94, v77, v107
	v_fmac_f32_e32 v94, v76, v104
	v_add_f32_e32 v93, v94, v93
	v_mul_f32_e32 v94, v79, v108
	v_fmac_f32_e32 v94, v78, v106
	v_add_f32_e32 v93, v94, v93
	ds_bpermute_b32 v110, v80, v109
	ds_bpermute_b32 v122, v80, v118
	ds_bpermute_b32 v123, v80, v119
	ds_bpermute_b32 v124, v80, v120
	ds_bpermute_b32 v94, v80, v93
	s_waitcnt lgkmcnt(0)
	v_add_f32_e32 v109, v109, v110
	v_add_f32_e32 v118, v118, v122
	v_add_f32_e32 v119, v119, v123
	v_add_f32_e32 v120, v120, v124
	v_add_f32_e32 v93, v93, v94
	ds_bpermute_b32 v110, v88, v109
	ds_bpermute_b32 v122, v88, v118
	ds_bpermute_b32 v123, v88, v119
	ds_bpermute_b32 v124, v88, v120
	ds_bpermute_b32 v94, v88, v93
	s_waitcnt lgkmcnt(0)
	v_add_f32_e32 v109, v109, v110
	v_add_f32_e32 v118, v118, v122
	v_add_f32_e32 v119, v119, v123
	v_add_f32_e32 v120, v120, v124
	v_add_f32_e32 v93, v93, v94
	ds_bpermute_b32 v110, v89, v109
	ds_bpermute_b32 v122, v89, v118
	ds_bpermute_b32 v123, v89, v119
	ds_bpermute_b32 v124, v89, v120
	ds_bpermute_b32 v94, v89, v93
	s_waitcnt lgkmcnt(0)
	v_add_f32_e32 v109, v109, v110
	v_add_f32_e32 v118, v118, v122
	v_add_f32_e32 v119, v119, v123
	v_add_f32_e32 v120, v120, v124
	v_add_f32_e32 v93, v93, v94
	ds_bpermute_b32 v110, v90, v109
	ds_bpermute_b32 v122, v90, v118
	ds_bpermute_b32 v123, v90, v119
	ds_bpermute_b32 v124, v90, v120
	ds_bpermute_b32 v94, v90, v93
	s_waitcnt lgkmcnt(0)
	v_add_f32_e32 v109, v109, v110
	v_add_f32_e32 v118, v118, v122
	v_add_f32_e32 v119, v119, v123
	v_add_f32_e32 v120, v120, v124
	v_add_f32_e32 v93, v93, v94
	ds_bpermute_b32 v110, v91, v109
	ds_bpermute_b32 v122, v91, v118
	ds_bpermute_b32 v123, v91, v119
	ds_bpermute_b32 v124, v91, v120
	ds_bpermute_b32 v94, v91, v93
	s_waitcnt lgkmcnt(0)
	v_add_f32_e32 v109, v109, v110
	v_add_f32_e32 v118, v118, v122
	v_add_f32_e32 v119, v119, v123
	v_add_f32_e32 v120, v120, v124
	v_add_f32_e32 v93, v93, v94
	ds_bpermute_b32 v110, v92, v109
	ds_bpermute_b32 v122, v92, v118
	ds_bpermute_b32 v123, v92, v119
	ds_bpermute_b32 v124, v92, v120
	ds_bpermute_b32 v94, v92, v93
	s_waitcnt lgkmcnt(0)
	v_add_f32_e32 v109, v109, v110
	v_add_f32_e32 v118, v118, v122
	v_add_f32_e32 v119, v119, v123
	v_add_f32_e32 v120, v120, v124
	v_add_f32_e32 v93, v93, v94
	s_and_saveexec_b64 s[26:27], vcc
	s_cbranch_execz .LBB0_179
	global_store_dword v81, v109, s[4:5]
	s_add_i32 s46, s38, s43
	s_ashr_i32 s47, s46, 31
	s_lshl_b64 s[46:47], s[46:47], 2
	s_add_u32 s46, s18, s46
	s_addc_u32 s47, s39, s47
	global_store_dword v81, v118, s[46:47]
	s_add_i32 s48, s40, s43
	s_ashr_i32 s49, s48, 31
	s_lshl_b64 s[48:49], s[48:49], 2
	s_add_u32 s48, s18, s48
	s_addc_u32 s49, s39, s49
	global_store_dword v81, v119, s[48:49]
	s_add_i32 s52, s41, s43
	s_ashr_i32 s53, s52, 31
	s_lshl_b64 s[52:53], s[52:53], 2
	s_add_u32 s52, s18, s52
	s_addc_u32 s53, s39, s53
	global_store_dword v81, v120, s[52:53]
	s_add_i32 s54, s42, s43
	s_ashr_i32 s55, s54, 31
	s_lshl_b64 s[54:55], s[54:55], 2
	s_add_u32 s54, s18, s54
	s_addc_u32 s55, s39, s55
	global_store_dword v81, v93, s[54:55]
	s_branch .LBB0_179
